# attention: score masks folded into per-group thresholds in an 8x-scaled score domain (bit-exact), V reads as ds_read_b64 pairs
# speedup vs baseline: 1.0862x; 1.0074x over previous
; #define LAS __attribute__((address_space(3)))
; __device__ void attn_mfma(const Params& p, int l, const bf16_t* proj, bf16_t* y0, LAS unsigned char* lds) {
;     ...
;             for (int q = 0; q < 6; ++q) { const int c = tid + q * NTHREADS, row = c >> 3, part = c & 7; *(LAS u32x4*)(Ks + row * KP + part * 8) = kreg[q]; }
; #pragma unroll
;             for (int q = 0; q < 3; ++q) { const int c = tid + q * NTHREADS, pr = c >> 3, part = c & 7; const u32x4 a = va[q], b = vb[q];
; #pragma unroll
;                 for (int e = 0; e < 4; ++e) {
;                     *(LAS unsigned*)(Vt + (part * 8 + 2 * e) * VP + pr * 2) = (a[e] & 0xffffu) | (b[e] << 16);
;                     *(LAS unsigned*)(Vt + (part * 8 + 2 * e + 1) * VP + pr * 2) = (a[e] >> 16) | (b[e] & 0xffff0000u); } }
;         }
;         const int hq = hk * 4 + (wv >> 1);
;         bf16x8 qn[2];
; #pragma unroll
;         for (int ks = 0; ks < 2; ++ks) qn[ks] = *(const bf16x8*)(proj + (size_t)(n * 128 + (wv & 1) * 64 + fr) * NP + AQ + hq * 64 + ks * 32 + g * 8);
;         __syncthreads();
;         const float slope = exp2f(-(float)(hq + 1)), sink = p.attn_sink[l * 8 + hq];
;         const bool edge = (n == 0) || (n == SEQ / 128 - 1);
.LBB0_477:
	s_or_b64 exec, exec, s[4:5]
	s_waitcnt vmcnt(0)
	ds_write_b128 v135, v[4:7]
	ds_write_b128 v136, v[0:3]
	ds_write_b128 v137, v[12:15]
	ds_write_b128 v138, v[8:11]
	ds_write_b128 v139, v[20:23]
	ds_write_b128 v140, v[16:19]
	v_and_b32_e32 v0, 0xffff, v28
	v_lshrrev_b32_e32 v1, 16, v28
	v_lshl_or_b32 v0, v32, 16, v0
	v_and_or_b32 v1, v32, s0, v1
	v_add_u32_e32 v2, 0xd800, v131
	ds_write2_b32 v2, v0, v1 offset1:196
	v_and_b32_e32 v0, 0xffff, v29
	v_lshrrev_b32_e32 v1, 16, v29
	v_lshl_or_b32 v0, v33, 16, v0
	v_and_or_b32 v1, v33, s0, v1
	v_add_u32_e32 v2, 0xde00, v131
	ds_write2_b32 v2, v0, v1 offset0:8 offset1:204
	v_and_b32_e32 v0, 0xffff, v30
	v_lshrrev_b32_e32 v1, 16, v30
	v_lshl_or_b32 v0, v34, 16, v0
	v_and_or_b32 v1, v34, s0, v1
	v_add_u32_e32 v2, 0xe400, v131
	ds_write2_b32 v2, v0, v1 offset0:16 offset1:212
	v_and_b32_e32 v0, 0xffff, v31
	v_lshrrev_b32_e32 v1, 16, v31
	v_lshl_or_b32 v0, v35, 16, v0
	v_and_or_b32 v1, v35, s0, v1
	v_add_u32_e32 v2, 0xea00, v131
	ds_write2_b32 v2, v0, v1 offset0:24 offset1:220
	v_and_b32_e32 v0, 0xffff, v24
	v_lshrrev_b32_e32 v1, 16, v24
	v_lshl_or_b32 v0, v36, 16, v0
	v_and_or_b32 v1, v36, s0, v1
	v_add_u32_e32 v2, 0xd800, v132
	ds_write2_b32 v2, v0, v1 offset1:196
	v_and_b32_e32 v0, 0xffff, v25
	v_lshrrev_b32_e32 v1, 16, v25
	v_lshl_or_b32 v0, v37, 16, v0
	v_and_or_b32 v1, v37, s0, v1
	v_add_u32_e32 v2, 0xde00, v132
	ds_write2_b32 v2, v0, v1 offset0:8 offset1:204
	v_and_b32_e32 v0, 0xffff, v26
	v_lshrrev_b32_e32 v1, 16, v26
	v_lshl_or_b32 v0, v38, 16, v0
	v_and_or_b32 v1, v38, s0, v1
	v_add_u32_e32 v2, 0xe400, v132
	ds_write2_b32 v2, v0, v1 offset0:16 offset1:212
	v_and_b32_e32 v0, 0xffff, v27
	v_lshrrev_b32_e32 v1, 16, v27
	v_lshl_or_b32 v0, v39, 16, v0
	v_and_or_b32 v1, v39, s0, v1
	v_add_u32_e32 v2, 0xea00, v132
	ds_write2_b32 v2, v0, v1 offset0:24 offset1:220
	v_and_b32_e32 v0, 0xffff, v40
	v_lshrrev_b32_e32 v1, 16, v40
	v_lshl_or_b32 v0, v44, 16, v0
	v_and_or_b32 v1, v44, s0, v1
	v_add_u32_e32 v2, 0xd800, v133
	ds_write2_b32 v2, v0, v1 offset1:196
	v_and_b32_e32 v0, 0xffff, v41
	v_lshrrev_b32_e32 v1, 16, v41
	v_lshl_or_b32 v0, v45, 16, v0
	v_and_or_b32 v1, v45, s0, v1
	v_add_u32_e32 v2, 0xde00, v133
	ds_write2_b32 v2, v0, v1 offset0:8 offset1:204
	v_and_b32_e32 v0, 0xffff, v42
	v_lshrrev_b32_e32 v1, 16, v42
	v_lshl_or_b32 v0, v46, 16, v0
	v_and_or_b32 v1, v46, s0, v1
	v_add_u32_e32 v2, 0xe400, v133
	ds_write2_b32 v2, v0, v1 offset0:16 offset1:212
	v_and_b32_e32 v0, 0xffff, v43
	v_lshrrev_b32_e32 v1, 16, v43
	v_lshl_add_u32 v6, s6, 2, v109
	v_lshl_or_b32 v0, v47, 16, v0
	v_and_or_b32 v1, v47, s0, v1
	v_add_u32_e32 v2, 0xea00, v133
	v_lshlrev_b32_e32 v114, 6, v6
	ds_write2_b32 v2, v0, v1 offset0:24 offset1:220
	v_or_b32_e32 v2, s13, v120
	v_mov_b64_e32 v[0:1], s[94:95]
	v_ashrrev_i32_e32 v115, 31, v114
	v_mad_i64_i32 v[0:1], s[4:5], v2, s63, v[0:1]
	v_lshlrev_b64 v[2:3], 1, v[114:115]
	v_lshl_add_u64 v[0:1], v[0:1], 0, v[2:3]
	v_lshlrev_b32_e32 v188, 1, v110
	v_lshl_add_u64 v[0:1], v[0:1], 0, v[188:189]
	v_lshl_add_u64 v[4:5], v[0:1], 0, s[24:25]
	v_add_co_u32_e32 v0, vcc, s66, v0
	v_readlane_b32 s40, v254, 48
	s_nop 0
	v_addc_co_u32_e32 v1, vcc, 0, v1, vcc
	global_load_dwordx4 v[100:103], v[0:1], off offset:2048
	global_load_dwordx4 v[8:11], v[4:5], off offset:64
	v_add_u32_e32 v0, s10, v6
	v_ashrrev_i32_e32 v1, 31, v0
	v_readlane_b32 s44, v254, 52
	v_readlane_b32 s45, v254, 53
	s_waitcnt lgkmcnt(0)
	s_barrier
	v_lshl_add_u64 v[0:1], v[0:1], 2, s[44:45]
	global_load_dword v146, v[0:1], off
	v_add_u32_e32 v0, 1, v6
	v_cvt_f32_i32_e32 v0, v0
	s_mov_b32 s4, 0x42fc0000
	s_cmp_gt_u32 s11, 1
	s_mov_b32 s12, 0
	v_cmp_lt_f32_e32 vcc, s4, v0
	s_cselect_b64 s[4:5], -1, 0
	s_cselect_b32 s16, s71, 0xbf800000
	s_cmp_lt_u32 s11, 2
	v_cndmask_b32_e32 v1, 0, v218, vcc
	v_sub_f32_e32 v0, v1, v0
	v_exp_f32_e32 v0, v0
	s_cselect_b64 s[6:7], -1, 0
	s_cmpk_lg_i32 s8, 0x7f
	s_cselect_b32 s17, s71, 0xbf800000
	v_cndmask_b32_e32 v1, 0, v219, vcc
	s_cselect_b64 s[8:9], -1, 0
	v_ldexp_f32 v147, v0, v1
	v_mul_f32_e32 v147, 0x41000000, v147
	s_and_b64 s[8:9], s[4:5], s[8:9]
	v_lshl_add_u64 v[116:117], v[112:113], 0, v[2:3]
	v_add_u32_e32 v148, s13, v120
	v_readlane_b32 s41, v254, 49
	v_readlane_b32 s42, v254, 50
	v_readlane_b32 s43, v254, 51
	v_readlane_b32 s46, v254, 54
	v_readlane_b32 s47, v254, 55
	v_readlane_b32 s48, v254, 56
	v_readlane_b32 s49, v254, 57
	v_readlane_b32 s50, v254, 58
	v_readlane_b32 s51, v254, 59
	v_readlane_b32 s52, v254, 60
	v_readlane_b32 s53, v254, 61
	v_readlane_b32 s54, v254, 62
	v_readlane_b32 s55, v254, 63
; #define LAS __attribute__((address_space(3)))
; __device__ void attn_mfma(const Params& p, int l, const bf16_t* proj, bf16_t* y0, LAS unsigned char* lds) {
;     ...
;         for (int tile = 0; tile < 4; ++tile) {
;             const int tl = (wv & 1) * 64 + tile * 16 + fr, t = n * 128 + tl;
;             bf16x8 qf[2];
; #pragma unroll
;             for (int ks = 0; ks < 2; ++ks) { qf[ks] = qn[ks]; qn[ks] = *(const bf16x8*)(proj + (size_t)(t + (tile < 3 ? 16 : 0)) * NP + AQ + hq * 64 + ks * 32 + g * 8); }
;             f32x4 sacc[24];
; #pragma unroll
;             for (int kt = 0; kt < 24; ++kt) { f32x4 a = {0.f, 0.f, 0.f, 0.f};
; #pragma unroll
;                 for (int ks = 0; ks < 2; ++ks) { const bf16x8 kf = *(const LAS bf16x8*)(Ks + (kt * 16 + fr) * KP + ks * 32 + g * 8); a = __builtin_amdgcn_mfma_f32_16x16x32_bf16(kf, qf[ks], a, 0, 0, 0); }
;                 sacc[kt] = a; if ((kt % 6) == 5) __builtin_amdgcn_sched_barrier(0); }
.LBB0_478:
	ds_read_b128 v[0:3], v141
	ds_read_b128 v[4:7], v141 offset:64
	ds_read_b128 v[12:15], v141 offset:2304
	ds_read_b128 v[16:19], v141 offset:2368
	s_cmp_eq_u32 s12, 48
	v_add_u32_e32 v118, s12, v148
	s_waitcnt vmcnt(2) lgkmcnt(3)
	v_mfma_f32_16x16x32_bf16 v[0:3], v[0:3], v[100:103], 0
	s_cselect_b32 s13, 0, 16
	v_add_u32_e32 v22, s13, v118
	v_mov_b64_e32 v[20:21], s[94:95]
	s_waitcnt lgkmcnt(1)
	v_mfma_f32_16x16x32_bf16 v[12:15], v[12:15], v[100:103], 0
	s_waitcnt vmcnt(1)
	v_mfma_f32_16x16x32_bf16 v[104:107], v[4:7], v[8:11], v[0:3]
	ds_read_b128 v[4:7], v141 offset:4672
	s_nop 1
	ds_read_b128 v[0:3], v141 offset:4608
	s_waitcnt lgkmcnt(2)
	v_mfma_f32_16x16x32_bf16 v[96:99], v[16:19], v[8:11], v[12:15]
	ds_read_b128 v[16:19], v141 offset:6976
	s_nop 1
	ds_read_b128 v[12:15], v141 offset:6912
	s_waitcnt lgkmcnt(2)
	v_mfma_f32_16x16x32_bf16 v[0:3], v[0:3], v[100:103], 0
	v_mfma_f32_16x16x32_bf16 v[92:95], v[4:7], v[8:11], v[0:3]
	s_waitcnt lgkmcnt(0)
	v_mfma_f32_16x16x32_bf16 v[4:7], v[12:15], v[100:103], 0
	s_nop 4
	ds_read_b128 v[0:3], v141 offset:9216
	ds_read_b128 v[12:15], v141 offset:9280
	v_mfma_f32_16x16x32_bf16 v[88:91], v[16:19], v[8:11], v[4:7]
	s_waitcnt lgkmcnt(1)
	v_mfma_f32_16x16x32_bf16 v[0:3], v[0:3], v[100:103], 0
	s_nop 0
	v_mad_i64_i32 v[4:5], s[14:15], v22, s63, v[20:21]
	v_lshl_add_u64 v[4:5], v[114:115], 1, v[4:5]
	v_lshl_add_u64 v[16:17], v[4:5], 0, v[188:189]
	ds_read_b128 v[4:7], v141 offset:11520
	v_add_co_u32_e32 v22, vcc, 0x1000, v16
	v_lshl_add_u64 v[20:21], v[16:17], 0, s[24:25]
	s_nop 0
	v_addc_co_u32_e32 v23, vcc, 0, v17, vcc
	s_waitcnt lgkmcnt(1)
	v_mfma_f32_16x16x32_bf16 v[84:87], v[12:15], v[8:11], v[0:3]
	ds_read_b128 v[12:15], v141 offset:11584
	s_waitcnt lgkmcnt(1)
	v_mfma_f32_16x16x32_bf16 v[16:19], v[4:7], v[100:103], 0
	global_load_dwordx4 v[0:3], v[22:23], off offset:2048
	global_load_dwordx4 v[4:7], v[20:21], off offset:64
	s_waitcnt lgkmcnt(0)
	v_mfma_f32_16x16x32_bf16 v[80:83], v[12:15], v[8:11], v[16:19]
	ds_read_b128 v[12:15], v141 offset:13824
	s_nop 2
	ds_read_b128 v[16:19], v141 offset:13888
	ds_read_b128 v[20:23], v141 offset:16128
	ds_read_b128 v[24:27], v141 offset:16192
	s_waitcnt lgkmcnt(3)
	v_mfma_f32_16x16x32_bf16 v[12:15], v[12:15], v[100:103], 0
	s_waitcnt lgkmcnt(2)
	v_mfma_f32_16x16x32_bf16 v[76:79], v[16:19], v[8:11], v[12:15]
	ds_read_b128 v[16:19], v141 offset:18496
	s_nop 4
	ds_read_b128 v[12:15], v141 offset:18432
	s_waitcnt lgkmcnt(3)
	v_mfma_f32_16x16x32_bf16 v[20:23], v[20:23], v[100:103], 0
	s_waitcnt lgkmcnt(2)
	v_mfma_f32_16x16x32_bf16 v[72:75], v[24:27], v[8:11], v[20:23]
	s_waitcnt lgkmcnt(0)
	v_mfma_f32_16x16x32_bf16 v[12:15], v[12:15], v[100:103], 0
	s_nop 3
	ds_read_b128 v[20:23], v141 offset:20736
	v_mfma_f32_16x16x32_bf16 v[68:71], v[16:19], v[8:11], v[12:15]
	s_nop 2
	ds_read_b128 v[12:15], v141 offset:20800
	s_waitcnt lgkmcnt(1)
	v_mfma_f32_16x16x32_bf16 v[16:19], v[20:23], v[100:103], 0
	ds_read_b128 v[20:23], v141 offset:23040
	s_waitcnt lgkmcnt(1)
	v_mfma_f32_16x16x32_bf16 v[64:67], v[12:15], v[8:11], v[16:19]
	ds_read_b128 v[12:15], v141 offset:23104
	s_waitcnt lgkmcnt(1)
	v_mfma_f32_16x16x32_bf16 v[16:19], v[20:23], v[100:103], 0
	ds_read_b128 v[20:23], v141 offset:25344
	s_waitcnt lgkmcnt(1)
	v_mfma_f32_16x16x32_bf16 v[60:63], v[12:15], v[8:11], v[16:19]
	ds_read_b128 v[12:15], v141 offset:25408
	s_waitcnt lgkmcnt(1)
	v_mfma_f32_16x16x32_bf16 v[16:19], v[20:23], v[100:103], 0
	s_waitcnt lgkmcnt(0)
	v_mfma_f32_16x16x32_bf16 v[56:59], v[12:15], v[8:11], v[16:19]
	ds_read_b128 v[12:15], v141 offset:27648
	s_nop 4
	ds_read_b128 v[16:19], v141 offset:27712
	ds_read_b128 v[20:23], v141 offset:29952
	ds_read_b128 v[24:27], v141 offset:30016
	s_waitcnt lgkmcnt(3)
	v_mfma_f32_16x16x32_bf16 v[12:15], v[12:15], v[100:103], 0
	s_waitcnt lgkmcnt(2)
	v_mfma_f32_16x16x32_bf16 v[52:55], v[16:19], v[8:11], v[12:15]
	ds_read_b128 v[16:19], v141 offset:32320
	s_nop 4
	ds_read_b128 v[12:15], v141 offset:32256
	s_waitcnt lgkmcnt(3)
	v_mfma_f32_16x16x32_bf16 v[20:23], v[20:23], v[100:103], 0
	s_waitcnt lgkmcnt(2)
	v_mfma_f32_16x16x32_bf16 v[48:51], v[24:27], v[8:11], v[20:23]
	s_waitcnt lgkmcnt(0)
	v_mfma_f32_16x16x32_bf16 v[12:15], v[12:15], v[100:103], 0
	s_nop 3
	ds_read_b128 v[20:23], v141 offset:34560
	v_mfma_f32_16x16x32_bf16 v[44:47], v[16:19], v[8:11], v[12:15]
	s_nop 2
	ds_read_b128 v[12:15], v141 offset:34624
	s_waitcnt lgkmcnt(1)
	v_mfma_f32_16x16x32_bf16 v[16:19], v[20:23], v[100:103], 0
	ds_read_b128 v[20:23], v141 offset:36864
	s_waitcnt lgkmcnt(1)
	v_mfma_f32_16x16x32_bf16 v[40:43], v[12:15], v[8:11], v[16:19]
	ds_read_b128 v[12:15], v141 offset:36928
	s_waitcnt lgkmcnt(1)
	v_mfma_f32_16x16x32_bf16 v[16:19], v[20:23], v[100:103], 0
	ds_read_b128 v[20:23], v141 offset:39168
	s_waitcnt lgkmcnt(1)
	v_mfma_f32_16x16x32_bf16 v[36:39], v[12:15], v[8:11], v[16:19]
	ds_read_b128 v[12:15], v141 offset:39232
	s_waitcnt lgkmcnt(1)
	v_mfma_f32_16x16x32_bf16 v[16:19], v[20:23], v[100:103], 0
	s_waitcnt lgkmcnt(0)
	v_mfma_f32_16x16x32_bf16 v[32:35], v[12:15], v[8:11], v[16:19]
	ds_read_b128 v[12:15], v141 offset:41472
	s_nop 4
	ds_read_b128 v[16:19], v141 offset:41536
	s_waitcnt lgkmcnt(1)
	v_mfma_f32_16x16x32_bf16 v[12:15], v[12:15], v[100:103], 0
	ds_read_b128 v[150:153], v141 offset:50752
	s_waitcnt lgkmcnt(1)
	v_mfma_f32_16x16x32_bf16 v[28:31], v[16:19], v[8:11], v[12:15]
	ds_read_b128 v[16:19], v141 offset:43840
	s_nop 3
	ds_read_b128 v[12:15], v141 offset:43776
	s_waitcnt lgkmcnt(0)
	v_mfma_f32_16x16x32_bf16 v[12:15], v[12:15], v[100:103], 0
	v_mfma_f32_16x16x32_bf16 v[24:27], v[16:19], v[8:11], v[12:15]
	ds_read_b128 v[16:19], v141 offset:46144
	s_nop 5
	ds_read_b128 v[12:15], v141 offset:46080
	s_waitcnt lgkmcnt(0)
; #define LAS __attribute__((address_space(3)))
; __device__ void attn_mfma(const Params& p, int l, const bf16_t* proj, bf16_t* y0, LAS unsigned char* lds) {
;     ...
;             for (int kt = 0; kt < 24; ++kt) { f32x4 a = {0.f, 0.f, 0.f, 0.f};
; #pragma unroll
;                 for (int ks = 0; ks < 2; ++ks) { const bf16x8 kf = *(const LAS bf16x8*)(Ks + (kt * 16 + fr) * KP + ks * 32 + g * 8); a = __builtin_amdgcn_mfma_f32_16x16x32_bf16(kf, qf[ks], a, 0, 0, 0); }
;                 sacc[kt] = a; if ((kt % 6) == 5) __builtin_amdgcn_sched_barrier(0); }
;             const float tq = (float)(tl + 128 - 4 * g);
;             float mx = sink;
; #pragma unroll
;             for (int kt = 0; kt < 24; ++kt)
; #pragma unroll
;                 for (int r = 0; r < 4; ++r) { const float x = (float)(kt * 16 + r) - tq; float sc = fmaf(sacc[kt][r], 0.125f, -slope * fabsf(x));
;                     bool valid = fabsf(x) <= 128.0f;
;                     if (edge) { const int kl = kt * 16 + 4 * g + r; valid = valid && (n == 0 ? kl >= 128 : kl < 256); }
;                     sc = valid ? sc : -1e30f; sacc[kt][r] = sc; mx = fmaxf(mx, sc); }
	v_mfma_f32_16x16x32_bf16 v[12:15], v[12:15], v[100:103], 0
	v_mfma_f32_16x16x32_bf16 v[20:23], v[16:19], v[8:11], v[12:15]
	ds_read_b128 v[16:19], v141 offset:48448
	s_nop 5
	ds_read_b128 v[12:15], v141 offset:48384
	s_waitcnt lgkmcnt(0)
	v_mfma_f32_16x16x32_bf16 v[12:15], v[12:15], v[100:103], 0
	v_mfma_f32_16x16x32_bf16 v[16:19], v[16:19], v[8:11], v[12:15]
	s_nop 6
	ds_read_b128 v[12:15], v141 offset:50688
	s_waitcnt lgkmcnt(0)
	v_mfma_f32_16x16x32_bf16 v[12:15], v[12:15], v[100:103], 0
	v_mfma_f32_16x16x32_bf16 v[12:15], v[150:153], v[8:11], v[12:15]
	ds_read_b128 v[150:153], v141 offset:52992
	s_waitcnt lgkmcnt(0)
	v_mfma_f32_16x16x32_bf16 v[100:103], v[150:153], v[100:103], 0
	ds_read_b128 v[150:153], v141 offset:53056
	s_waitcnt lgkmcnt(0)
	v_mfma_f32_16x16x32_bf16 v[8:11], v[150:153], v[8:11], v[100:103]
	s_nop 4
	v_add_u32_e32 v155, s12, v134
	v_cvt_f32_u32_e32 v101, v155
	s_waitcnt vmcnt(2)
	v_mul_f32_e32 v154, 0x41000000, v146
	v_sub_f32_e32 v150, 0, v101
	v_sub_f32_e32 v151, 1.0, v101
	v_sub_f32_e32 v152, 2.0, v101
	v_sub_f32_e32 v153, 0x40400000, v101
	v_cmp_le_f32_e64 vcc, |v150|, s16
	v_fma_f32 v104, |v150|, -v147, v104
	v_cmp_le_f32_e64 s[14:15], |v151|, s16
	v_cndmask_b32_e32 v100, v220, v104, vcc
	v_fma_f32 v105, |v151|, -v147, v105
	v_cmp_le_f32_e64 vcc, |v152|, s16
	v_cndmask_b32_e64 v102, v220, v105, s[14:15]
	v_fma_f32 v106, |v152|, -v147, v106
	v_cmp_le_f32_e64 s[14:15], |v153|, s16
	v_cndmask_b32_e32 v103, v220, v106, vcc
	v_fma_f32 v107, |v153|, -v147, v107
	v_max3_f32 v154, v154, v100, v102
	v_cndmask_b32_e64 v104, v220, v107, s[14:15]
	v_max3_f32 v154, v154, v103, v104
	v_sub_f32_e32 v150, 0x41800000, v101
	v_sub_f32_e32 v151, 0x41880000, v101
	v_sub_f32_e32 v152, 0x41900000, v101
	v_sub_f32_e32 v153, 0x41980000, v101
	v_cmp_le_f32_e64 vcc, |v150|, s16
	v_fma_f32 v96, |v150|, -v147, v96
	v_cmp_le_f32_e64 s[14:15], |v151|, s16
	v_cndmask_b32_e32 v96, v220, v96, vcc
	v_fma_f32 v97, |v151|, -v147, v97
	v_cmp_le_f32_e64 vcc, |v152|, s16
	v_cndmask_b32_e64 v97, v220, v97, s[14:15]
	v_fma_f32 v98, |v152|, -v147, v98
	v_cmp_le_f32_e64 s[14:15], |v153|, s16
	v_cndmask_b32_e32 v98, v220, v98, vcc
	v_fma_f32 v99, |v153|, -v147, v99
	v_max3_f32 v154, v154, v96, v97
	v_cndmask_b32_e64 v99, v220, v99, s[14:15]
	v_max3_f32 v154, v154, v98, v99
	v_sub_f32_e32 v150, 0x42000000, v101
	v_sub_f32_e32 v151, 0x42040000, v101
	v_sub_f32_e32 v152, 0x42080000, v101
	v_sub_f32_e32 v153, 0x420c0000, v101
	v_cmp_le_f32_e64 vcc, |v150|, s16
	v_fma_f32 v92, |v150|, -v147, v92
	v_cmp_le_f32_e64 s[14:15], |v151|, s16
	v_cndmask_b32_e32 v92, v220, v92, vcc
	v_fma_f32 v93, |v151|, -v147, v93
	v_cmp_le_f32_e64 vcc, |v152|, s16
	v_cndmask_b32_e64 v93, v220, v93, s[14:15]
	v_fma_f32 v94, |v152|, -v147, v94
	v_cmp_le_f32_e64 s[14:15], |v153|, s16
	v_cndmask_b32_e32 v94, v220, v94, vcc
	v_fma_f32 v95, |v153|, -v147, v95
	v_max3_f32 v154, v154, v92, v93
	v_cndmask_b32_e64 v95, v220, v95, s[14:15]
	v_max3_f32 v154, v154, v94, v95
	v_sub_f32_e32 v150, 0x42400000, v101
	v_sub_f32_e32 v151, 0x42440000, v101
	v_sub_f32_e32 v152, 0x42480000, v101
	v_sub_f32_e32 v153, 0x424c0000, v101
	v_cmp_le_f32_e64 vcc, |v150|, s16
	v_fma_f32 v88, |v150|, -v147, v88
	v_cmp_le_f32_e64 s[14:15], |v151|, s16
	v_cndmask_b32_e32 v88, v220, v88, vcc
	v_fma_f32 v89, |v151|, -v147, v89
	v_cmp_le_f32_e64 vcc, |v152|, s16
	v_cndmask_b32_e64 v89, v220, v89, s[14:15]
	v_fma_f32 v90, |v152|, -v147, v90
	v_cmp_le_f32_e64 s[14:15], |v153|, s16
	v_cndmask_b32_e32 v90, v220, v90, vcc
	v_fma_f32 v91, |v153|, -v147, v91
	v_max3_f32 v154, v154, v88, v89
	v_cndmask_b32_e64 v91, v220, v91, s[14:15]
	v_max3_f32 v154, v154, v90, v91
	v_sub_f32_e32 v150, 0x42800000, v101
	v_sub_f32_e32 v151, 0x42820000, v101
	v_sub_f32_e32 v152, 0x42840000, v101
	v_sub_f32_e32 v153, 0x42860000, v101
	v_cmp_le_f32_e64 vcc, |v150|, s16
	v_fma_f32 v84, |v150|, -v147, v84
	v_cmp_le_f32_e64 s[14:15], |v151|, s16
	v_cndmask_b32_e32 v84, v220, v84, vcc
	v_fma_f32 v85, |v151|, -v147, v85
	v_cmp_le_f32_e64 vcc, |v152|, s16
	v_cndmask_b32_e64 v85, v220, v85, s[14:15]
	v_fma_f32 v86, |v152|, -v147, v86
	v_cmp_le_f32_e64 s[14:15], |v153|, s16
	v_cndmask_b32_e32 v86, v220, v86, vcc
	v_fma_f32 v87, |v153|, -v147, v87
	v_max3_f32 v154, v154, v84, v85
	v_cndmask_b32_e64 v87, v220, v87, s[14:15]
	v_max3_f32 v154, v154, v86, v87
	v_sub_f32_e32 v150, 0x42a00000, v101
	v_sub_f32_e32 v151, 0x42a20000, v101
	v_sub_f32_e32 v152, 0x42a40000, v101
	v_sub_f32_e32 v153, 0x42a60000, v101
	v_cmp_le_f32_e64 vcc, |v150|, s16
	v_fma_f32 v80, |v150|, -v147, v80
	v_cmp_le_f32_e64 s[14:15], |v151|, s16
	v_cndmask_b32_e32 v80, v220, v80, vcc
	v_fma_f32 v81, |v151|, -v147, v81
	v_cmp_le_f32_e64 vcc, |v152|, s16
	v_cndmask_b32_e64 v81, v220, v81, s[14:15]
	v_fma_f32 v82, |v152|, -v147, v82
	v_cmp_le_f32_e64 s[14:15], |v153|, s16
	v_cndmask_b32_e32 v82, v220, v82, vcc
	v_fma_f32 v83, |v153|, -v147, v83
	v_max3_f32 v154, v154, v80, v81
	v_cndmask_b32_e64 v83, v220, v83, s[14:15]
	v_max3_f32 v154, v154, v82, v83
	v_sub_f32_e32 v150, 0x42c00000, v101
	v_sub_f32_e32 v151, 0x42c20000, v101
	v_sub_f32_e32 v152, 0x42c40000, v101
	v_sub_f32_e32 v153, 0x42c60000, v101
	v_cmp_le_f32_e64 vcc, |v150|, s16
	v_fma_f32 v76, |v150|, -v147, v76
	v_cmp_le_f32_e64 s[14:15], |v151|, s16
	v_cndmask_b32_e32 v76, v220, v76, vcc
	v_fma_f32 v77, |v151|, -v147, v77
	v_cmp_le_f32_e64 vcc, |v152|, s16
	v_cndmask_b32_e64 v77, v220, v77, s[14:15]
	v_fma_f32 v78, |v152|, -v147, v78
	v_cmp_le_f32_e64 s[14:15], |v153|, s16
	v_cndmask_b32_e32 v78, v220, v78, vcc
	v_fma_f32 v79, |v153|, -v147, v79
	v_max3_f32 v154, v154, v76, v77
	v_cndmask_b32_e64 v79, v220, v79, s[14:15]
; __device__ void attn_mfma(const Params& p, int l, const bf16_t* proj, bf16_t* y0, LAS unsigned char* lds) {
;     ...
;             for (int kt = 0; kt < 24; ++kt)
; #pragma unroll
;                 for (int r = 0; r < 4; ++r) { const float x = (float)(kt * 16 + r) - tq; float sc = fmaf(sacc[kt][r], 0.125f, -slope * fabsf(x));
;                     bool valid = fabsf(x) <= 128.0f;
;                     if (edge) { const int kl = kt * 16 + 4 * g + r; valid = valid && (n == 0 ? kl >= 128 : kl < 256); }
;                     sc = valid ? sc : -1e30f; sacc[kt][r] = sc; mx = fmaxf(mx, sc); }
	v_max3_f32 v154, v154, v78, v79
	v_sub_f32_e32 v150, 0x42e00000, v101
	v_sub_f32_e32 v151, 0x42e20000, v101
	v_sub_f32_e32 v152, 0x42e40000, v101
	v_sub_f32_e32 v153, 0x42e60000, v101
	v_cmp_le_f32_e64 vcc, |v150|, s16
	v_fma_f32 v72, |v150|, -v147, v72
	v_cmp_le_f32_e64 s[14:15], |v151|, s16
	v_cndmask_b32_e32 v72, v220, v72, vcc
	v_fma_f32 v73, |v151|, -v147, v73
	v_cmp_le_f32_e64 vcc, |v152|, s16
	v_cndmask_b32_e64 v73, v220, v73, s[14:15]
	v_fma_f32 v74, |v152|, -v147, v74
	v_cmp_le_f32_e64 s[14:15], |v153|, s16
	v_cndmask_b32_e32 v105, v220, v74, vcc
	v_fma_f32 v75, |v153|, -v147, v75
	v_max3_f32 v154, v154, v72, v73
	v_cndmask_b32_e64 v107, v220, v75, s[14:15]
	v_max3_f32 v154, v154, v105, v107
	v_sub_f32_e32 v150, 0x43000000, v101
	v_sub_f32_e32 v151, 0x43010000, v101
	v_sub_f32_e32 v152, 0x43020000, v101
	v_sub_f32_e32 v153, 0x43030000, v101
	v_cmp_le_f32_e64 vcc, |v150|, s71
	v_fma_f32 v68, |v150|, -v147, v68
	v_cmp_le_f32_e64 s[14:15], |v151|, s71
	v_cndmask_b32_e32 v106, v220, v68, vcc
	v_fma_f32 v69, |v151|, -v147, v69
	v_cmp_le_f32_e64 vcc, |v152|, s71
	v_cndmask_b32_e64 v75, v220, v69, s[14:15]
	v_fma_f32 v70, |v152|, -v147, v70
	v_cmp_le_f32_e64 s[14:15], |v153|, s71
	v_cndmask_b32_e32 v74, v220, v70, vcc
	v_fma_f32 v71, |v153|, -v147, v71
	v_max3_f32 v154, v154, v106, v75
	v_cndmask_b32_e64 v71, v220, v71, s[14:15]
	v_max3_f32 v154, v154, v74, v71
	v_sub_f32_e32 v150, 0x43100000, v101
	v_sub_f32_e32 v151, 0x43110000, v101
	v_sub_f32_e32 v152, 0x43120000, v101
	v_sub_f32_e32 v153, 0x43130000, v101
	v_cmp_le_f32_e64 vcc, |v150|, s71
	v_fma_f32 v64, |v150|, -v147, v64
	v_cmp_le_f32_e64 s[14:15], |v151|, s71
	v_cndmask_b32_e32 v70, v220, v64, vcc
	v_fma_f32 v65, |v151|, -v147, v65
	v_cmp_le_f32_e64 vcc, |v152|, s71
	v_cndmask_b32_e64 v69, v220, v65, s[14:15]
	v_fma_f32 v66, |v152|, -v147, v66
	v_cmp_le_f32_e64 s[14:15], |v153|, s71
	v_cndmask_b32_e32 v68, v220, v66, vcc
	v_fma_f32 v67, |v153|, -v147, v67
	v_max3_f32 v154, v154, v70, v69
	v_cndmask_b32_e64 v67, v220, v67, s[14:15]
	v_max3_f32 v154, v154, v68, v67
	v_sub_f32_e32 v150, 0x43200000, v101
	v_sub_f32_e32 v151, 0x43210000, v101
	v_sub_f32_e32 v152, 0x43220000, v101
	v_sub_f32_e32 v153, 0x43230000, v101
	v_cmp_le_f32_e64 vcc, |v150|, s71
	v_fma_f32 v60, |v150|, -v147, v60
	v_cmp_le_f32_e64 s[14:15], |v151|, s71
	v_cndmask_b32_e32 v66, v220, v60, vcc
	v_fma_f32 v61, |v151|, -v147, v61
	v_cmp_le_f32_e64 vcc, |v152|, s71
	v_cndmask_b32_e64 v65, v220, v61, s[14:15]
	v_fma_f32 v62, |v152|, -v147, v62
	v_cmp_le_f32_e64 s[14:15], |v153|, s71
	v_cndmask_b32_e32 v64, v220, v62, vcc
	v_fma_f32 v63, |v153|, -v147, v63
	v_max3_f32 v154, v154, v66, v65
	v_cndmask_b32_e64 v63, v220, v63, s[14:15]
	v_max3_f32 v154, v154, v64, v63
	v_sub_f32_e32 v150, 0x43300000, v101
	v_sub_f32_e32 v151, 0x43310000, v101
	v_sub_f32_e32 v152, 0x43320000, v101
	v_sub_f32_e32 v153, 0x43330000, v101
	v_cmp_le_f32_e64 vcc, |v150|, s71
	v_fma_f32 v56, |v150|, -v147, v56
	v_cmp_le_f32_e64 s[14:15], |v151|, s71
	v_cndmask_b32_e32 v62, v220, v56, vcc
	v_fma_f32 v57, |v151|, -v147, v57
	v_cmp_le_f32_e64 vcc, |v152|, s71
	v_cndmask_b32_e64 v61, v220, v57, s[14:15]
	v_fma_f32 v58, |v152|, -v147, v58
	v_cmp_le_f32_e64 s[14:15], |v153|, s71
	v_cndmask_b32_e32 v60, v220, v58, vcc
	v_fma_f32 v59, |v153|, -v147, v59
	v_max3_f32 v154, v154, v62, v61
	v_cndmask_b32_e64 v59, v220, v59, s[14:15]
	v_max3_f32 v154, v154, v60, v59
	v_sub_f32_e32 v150, 0x43400000, v101
	v_sub_f32_e32 v151, 0x43410000, v101
	v_sub_f32_e32 v152, 0x43420000, v101
	v_sub_f32_e32 v153, 0x43430000, v101
	v_cmp_le_f32_e64 vcc, |v150|, s71
	v_fma_f32 v52, |v150|, -v147, v52
	v_cmp_le_f32_e64 s[14:15], |v151|, s71
	v_cndmask_b32_e32 v58, v220, v52, vcc
	v_fma_f32 v53, |v151|, -v147, v53
	v_cmp_le_f32_e64 vcc, |v152|, s71
	v_cndmask_b32_e64 v57, v220, v53, s[14:15]
	v_fma_f32 v54, |v152|, -v147, v54
	v_cmp_le_f32_e64 s[14:15], |v153|, s71
	v_cndmask_b32_e32 v56, v220, v54, vcc
	v_fma_f32 v55, |v153|, -v147, v55
	v_max3_f32 v154, v154, v58, v57
	v_cndmask_b32_e64 v55, v220, v55, s[14:15]
	v_max3_f32 v154, v154, v56, v55
	v_sub_f32_e32 v150, 0x43500000, v101
	v_sub_f32_e32 v151, 0x43510000, v101
	v_sub_f32_e32 v152, 0x43520000, v101
	v_sub_f32_e32 v153, 0x43530000, v101
	v_cmp_le_f32_e64 vcc, |v150|, s71
	v_fma_f32 v48, |v150|, -v147, v48
	v_cmp_le_f32_e64 s[14:15], |v151|, s71
	v_cndmask_b32_e32 v54, v220, v48, vcc
	v_fma_f32 v49, |v151|, -v147, v49
	v_cmp_le_f32_e64 vcc, |v152|, s71
	v_cndmask_b32_e64 v53, v220, v49, s[14:15]
	v_fma_f32 v50, |v152|, -v147, v50
	v_cmp_le_f32_e64 s[14:15], |v153|, s71
	v_cndmask_b32_e32 v52, v220, v50, vcc
	v_fma_f32 v51, |v153|, -v147, v51
	v_max3_f32 v154, v154, v54, v53
	v_cndmask_b32_e64 v51, v220, v51, s[14:15]
	v_max3_f32 v154, v154, v52, v51
	v_sub_f32_e32 v150, 0x43600000, v101
	v_sub_f32_e32 v151, 0x43610000, v101
	v_sub_f32_e32 v152, 0x43620000, v101
	v_sub_f32_e32 v153, 0x43630000, v101
	v_cmp_le_f32_e64 vcc, |v150|, s71
	v_fma_f32 v44, |v150|, -v147, v44
	v_cmp_le_f32_e64 s[14:15], |v151|, s71
	v_cndmask_b32_e32 v50, v220, v44, vcc
	v_fma_f32 v45, |v151|, -v147, v45
	v_cmp_le_f32_e64 vcc, |v152|, s71
	v_cndmask_b32_e64 v49, v220, v45, s[14:15]
	v_fma_f32 v46, |v152|, -v147, v46
	v_cmp_le_f32_e64 s[14:15], |v153|, s71
	v_cndmask_b32_e32 v48, v220, v46, vcc
	v_fma_f32 v47, |v153|, -v147, v47
	v_max3_f32 v154, v154, v50, v49
	v_cndmask_b32_e64 v46, v220, v47, s[14:15]
	v_max3_f32 v154, v154, v48, v46
	v_sub_f32_e32 v150, 0x43700000, v101
	v_sub_f32_e32 v151, 0x43710000, v101
	v_sub_f32_e32 v152, 0x43720000, v101
	v_sub_f32_e32 v153, 0x43730000, v101
	v_cmp_le_f32_e64 vcc, |v150|, s71
	v_fma_f32 v40, |v150|, -v147, v40
; __device__ void attn_mfma(const Params& p, int l, const bf16_t* proj, bf16_t* y0, LAS unsigned char* lds) {
;     ...
;             for (int kt = 0; kt < 24; ++kt)
; #pragma unroll
;                 for (int r = 0; r < 4; ++r) { const float x = (float)(kt * 16 + r) - tq; float sc = fmaf(sacc[kt][r], 0.125f, -slope * fabsf(x));
;                     bool valid = fabsf(x) <= 128.0f;
;                     if (edge) { const int kl = kt * 16 + 4 * g + r; valid = valid && (n == 0 ? kl >= 128 : kl < 256); }
;                     sc = valid ? sc : -1e30f; sacc[kt][r] = sc; mx = fmaxf(mx, sc); }
;             mx = fmaxf(mx, __shfl_xor(mx, 16)); mx = fmaxf(mx, __shfl_xor(mx, 32));
	v_cmp_le_f32_e64 s[14:15], |v151|, s71
	v_cndmask_b32_e32 v45, v220, v40, vcc
	v_fma_f32 v41, |v151|, -v147, v41
	v_cmp_le_f32_e64 vcc, |v152|, s71
	v_cndmask_b32_e64 v44, v220, v41, s[14:15]
	v_fma_f32 v42, |v152|, -v147, v42
	v_cmp_le_f32_e64 s[14:15], |v153|, s71
	v_cndmask_b32_e32 v41, v220, v42, vcc
	v_fma_f32 v43, |v153|, -v147, v43
	v_max3_f32 v154, v154, v45, v44
	v_cndmask_b32_e64 v40, v220, v43, s[14:15]
	v_max3_f32 v154, v154, v41, v40
	v_sub_f32_e32 v150, 0x43800000, v101
	v_sub_f32_e32 v151, 0x43808000, v101
	v_sub_f32_e32 v152, 0x43810000, v101
	v_sub_f32_e32 v153, 0x43818000, v101
	v_cmp_le_f32_e64 vcc, |v150|, s17
	v_fma_f32 v36, |v150|, -v147, v36
	v_cmp_le_f32_e64 s[14:15], |v151|, s17
	v_cndmask_b32_e32 v36, v220, v36, vcc
	v_fma_f32 v37, |v151|, -v147, v37
	v_cmp_le_f32_e64 vcc, |v152|, s17
	v_cndmask_b32_e64 v37, v220, v37, s[14:15]
	v_fma_f32 v38, |v152|, -v147, v38
	v_cmp_le_f32_e64 s[14:15], |v153|, s17
	v_cndmask_b32_e32 v38, v220, v38, vcc
	v_fma_f32 v39, |v153|, -v147, v39
	v_max3_f32 v154, v154, v36, v37
	v_cndmask_b32_e64 v39, v220, v39, s[14:15]
	v_max3_f32 v154, v154, v38, v39
	v_sub_f32_e32 v150, 0x43880000, v101
	v_sub_f32_e32 v151, 0x43888000, v101
	v_sub_f32_e32 v152, 0x43890000, v101
	v_sub_f32_e32 v153, 0x43898000, v101
	v_cmp_le_f32_e64 vcc, |v150|, s17
	v_fma_f32 v32, |v150|, -v147, v32
	v_cmp_le_f32_e64 s[14:15], |v151|, s17
	v_cndmask_b32_e32 v32, v220, v32, vcc
	v_fma_f32 v33, |v151|, -v147, v33
	v_cmp_le_f32_e64 vcc, |v152|, s17
	v_cndmask_b32_e64 v33, v220, v33, s[14:15]
	v_fma_f32 v34, |v152|, -v147, v34
	v_cmp_le_f32_e64 s[14:15], |v153|, s17
	v_cndmask_b32_e32 v34, v220, v34, vcc
	v_fma_f32 v35, |v153|, -v147, v35
	v_max3_f32 v154, v154, v32, v33
	v_cndmask_b32_e64 v35, v220, v35, s[14:15]
	v_max3_f32 v154, v154, v34, v35
	v_sub_f32_e32 v150, 0x43900000, v101
	v_sub_f32_e32 v151, 0x43908000, v101
	v_sub_f32_e32 v152, 0x43910000, v101
	v_sub_f32_e32 v153, 0x43918000, v101
	v_cmp_le_f32_e64 vcc, |v150|, s17
	v_fma_f32 v28, |v150|, -v147, v28
	v_cmp_le_f32_e64 s[14:15], |v151|, s17
	v_cndmask_b32_e32 v28, v220, v28, vcc
	v_fma_f32 v29, |v151|, -v147, v29
	v_cmp_le_f32_e64 vcc, |v152|, s17
	v_cndmask_b32_e64 v29, v220, v29, s[14:15]
	v_fma_f32 v30, |v152|, -v147, v30
	v_cmp_le_f32_e64 s[14:15], |v153|, s17
	v_cndmask_b32_e32 v30, v220, v30, vcc
	v_fma_f32 v31, |v153|, -v147, v31
	v_max3_f32 v154, v154, v28, v29
	v_cndmask_b32_e64 v31, v220, v31, s[14:15]
	v_max3_f32 v154, v154, v30, v31
	v_sub_f32_e32 v150, 0x43980000, v101
	v_sub_f32_e32 v151, 0x43988000, v101
	v_sub_f32_e32 v152, 0x43990000, v101
	v_sub_f32_e32 v153, 0x43998000, v101
	v_cmp_le_f32_e64 vcc, |v150|, s17
	v_fma_f32 v24, |v150|, -v147, v24
	v_cmp_le_f32_e64 s[14:15], |v151|, s17
	v_cndmask_b32_e32 v24, v220, v24, vcc
	v_fma_f32 v25, |v151|, -v147, v25
	v_cmp_le_f32_e64 vcc, |v152|, s17
	v_cndmask_b32_e64 v25, v220, v25, s[14:15]
	v_fma_f32 v26, |v152|, -v147, v26
	v_cmp_le_f32_e64 s[14:15], |v153|, s17
	v_cndmask_b32_e32 v26, v220, v26, vcc
	v_fma_f32 v27, |v153|, -v147, v27
	v_max3_f32 v154, v154, v24, v25
	v_cndmask_b32_e64 v27, v220, v27, s[14:15]
	v_max3_f32 v154, v154, v26, v27
	v_sub_f32_e32 v150, 0x43a00000, v101
	v_sub_f32_e32 v151, 0x43a08000, v101
	v_sub_f32_e32 v152, 0x43a10000, v101
	v_sub_f32_e32 v153, 0x43a18000, v101
	v_cmp_le_f32_e64 vcc, |v150|, s17
	v_fma_f32 v20, |v150|, -v147, v20
	v_cmp_le_f32_e64 s[14:15], |v151|, s17
	v_cndmask_b32_e32 v20, v220, v20, vcc
	v_fma_f32 v21, |v151|, -v147, v21
	v_cmp_le_f32_e64 vcc, |v152|, s17
	v_cndmask_b32_e64 v21, v220, v21, s[14:15]
	v_fma_f32 v22, |v152|, -v147, v22
	v_cmp_le_f32_e64 s[14:15], |v153|, s17
	v_cndmask_b32_e32 v22, v220, v22, vcc
	v_fma_f32 v23, |v153|, -v147, v23
	v_max3_f32 v154, v154, v20, v21
	v_cndmask_b32_e64 v23, v220, v23, s[14:15]
	v_max3_f32 v154, v154, v22, v23
	v_sub_f32_e32 v150, 0x43a80000, v101
	v_sub_f32_e32 v151, 0x43a88000, v101
	v_sub_f32_e32 v152, 0x43a90000, v101
	v_sub_f32_e32 v153, 0x43a98000, v101
	v_cmp_le_f32_e64 vcc, |v150|, s17
	v_fma_f32 v16, |v150|, -v147, v16
	v_cmp_le_f32_e64 s[14:15], |v151|, s17
	v_cndmask_b32_e32 v16, v220, v16, vcc
	v_fma_f32 v17, |v151|, -v147, v17
	v_cmp_le_f32_e64 vcc, |v152|, s17
	v_cndmask_b32_e64 v17, v220, v17, s[14:15]
	v_fma_f32 v18, |v152|, -v147, v18
	v_cmp_le_f32_e64 s[14:15], |v153|, s17
	v_cndmask_b32_e32 v18, v220, v18, vcc
	v_fma_f32 v19, |v153|, -v147, v19
	v_max3_f32 v154, v154, v16, v17
	v_cndmask_b32_e64 v19, v220, v19, s[14:15]
	v_max3_f32 v154, v154, v18, v19
	v_sub_f32_e32 v150, 0x43b00000, v101
	v_sub_f32_e32 v151, 0x43b08000, v101
	v_sub_f32_e32 v152, 0x43b10000, v101
	v_sub_f32_e32 v153, 0x43b18000, v101
	v_cmp_le_f32_e64 vcc, |v150|, s17
	v_fma_f32 v12, |v150|, -v147, v12
	v_cmp_le_f32_e64 s[14:15], |v151|, s17
	v_cndmask_b32_e32 v12, v220, v12, vcc
	v_fma_f32 v13, |v151|, -v147, v13
	v_cmp_le_f32_e64 vcc, |v152|, s17
	v_cndmask_b32_e64 v13, v220, v13, s[14:15]
	v_fma_f32 v14, |v152|, -v147, v14
	v_cmp_le_f32_e64 s[14:15], |v153|, s17
	v_cndmask_b32_e32 v14, v220, v14, vcc
	v_fma_f32 v15, |v153|, -v147, v15
	v_max3_f32 v154, v154, v12, v13
	v_cndmask_b32_e64 v15, v220, v15, s[14:15]
	v_max3_f32 v154, v154, v14, v15
	v_sub_f32_e32 v150, 0x43b80000, v101
	v_sub_f32_e32 v151, 0x43b88000, v101
	v_sub_f32_e32 v152, 0x43b90000, v101
	v_sub_f32_e32 v153, 0x43b98000, v101
	v_cmp_le_f32_e64 vcc, |v150|, s17
	v_fma_f32 v8, |v150|, -v147, v8
	v_cmp_le_f32_e64 s[14:15], |v151|, s17
	v_cndmask_b32_e32 v42, v220, v8, vcc
	v_fma_f32 v9, |v151|, -v147, v9
	v_cmp_le_f32_e64 vcc, |v152|, s17
	v_cndmask_b32_e64 v43, v220, v9, s[14:15]
	v_fma_f32 v10, |v152|, -v147, v10
	v_cmp_le_f32_e64 s[14:15], |v153|, s17
	v_cndmask_b32_e32 v10, v220, v10, vcc
	v_fma_f32 v11, |v153|, -v147, v11
	v_max3_f32 v154, v154, v42, v43
	v_cndmask_b32_e64 v47, v220, v11, s[14:15]
	v_max3_f32 v8, v154, v10, v47
	v_mov_b32_e32 v9, v8
	s_waitcnt lgkmcnt(0)
; __device__ void attn_mfma(const Params& p, int l, const bf16_t* proj, bf16_t* y0, LAS unsigned char* lds) {
;     ...
;             mx = fmaxf(mx, __shfl_xor(mx, 16)); mx = fmaxf(mx, __shfl_xor(mx, 32));
;             float sum = 0.f; const float mxl = mx * 1.44269504f;
; #pragma unroll
;             for (int kt = 0; kt < 24; ++kt)
; #pragma unroll
;                 for (int r = 0; r < 4; ++r) { const float pr = exp2f(fmaf(sacc[kt][r], 1.44269504f, -mxl)); sacc[kt][r] = pr; sum += pr; }
	s_nop 1
	v_permlane16_swap_b32_e32 v9, v8
	v_max_f32_e32 v8, v8, v9
	v_mov_b32_e32 v9, v8
	s_waitcnt lgkmcnt(0)
	s_nop 1
	v_permlane32_swap_b32_e32 v9, v8
	v_max_f32_e32 v8, v8, v9
	v_mul_f32_e32 v119, 0xbe38aa3b, v8
	v_fmamk_f32 v9, v100, 0x3e38aa3b, v119
	v_fmamk_f32 v101, v103, 0x3e38aa3b, v119
	v_fmamk_f32 v96, v96, 0x3e38aa3b, v119
	v_exp_f32_e32 v9, v9
	v_fmamk_f32 v97, v97, 0x3e38aa3b, v119
	v_fmamk_f32 v98, v98, 0x3e38aa3b, v119
	v_fmamk_f32 v11, v102, 0x3e38aa3b, v119
	v_fmamk_f32 v99, v99, 0x3e38aa3b, v119
	v_fmamk_f32 v92, v92, 0x3e38aa3b, v119
	v_exp_f32_e32 v11, v11
	v_fmamk_f32 v94, v94, 0x3e38aa3b, v119
	v_exp_f32_e32 v101, v101
	v_mov_b32_e32 v100, v11
	v_add_f32_e32 v11, v9, v100
	v_fmamk_f32 v102, v104, 0x3e38aa3b, v119
	v_add_f32_e32 v11, v101, v11
	v_fmamk_f32 v95, v95, 0x3e38aa3b, v119
	v_exp_f32_e32 v102, v102
	v_fmamk_f32 v88, v88, 0x3e38aa3b, v119
	v_exp_f32_e32 v96, v96
	v_add_f32_e32 v11, v102, v11
	v_exp_f32_e32 v97, v97
	v_add_f32_e32 v11, v96, v11
	v_exp_f32_e32 v98, v98
	v_add_f32_e32 v11, v97, v11
	v_exp_f32_e32 v99, v99
	v_add_f32_e32 v11, v98, v11
	v_exp_f32_e32 v92, v92
	v_add_f32_e32 v103, v99, v11
	v_mov_b32_e32 v11, v92
	v_fmamk_f32 v92, v93, 0x3e38aa3b, v119
	v_add_f32_e32 v103, v11, v103
	v_fmamk_f32 v89, v89, 0x3e38aa3b, v119
	v_exp_f32_e32 v92, v92
	v_fmamk_f32 v90, v90, 0x3e38aa3b, v119
	v_exp_f32_e32 v94, v94
	v_add_f32_e32 v103, v92, v103
	v_mov_b32_e32 v93, v94
	v_add_f32_e32 v94, v93, v103
	v_fmamk_f32 v91, v91, 0x3e38aa3b, v119
	v_exp_f32_e32 v95, v95
	v_fmamk_f32 v84, v84, 0x3e38aa3b, v119
	v_fmamk_f32 v85, v85, 0x3e38aa3b, v119
	v_exp_f32_e32 v104, v88
	v_mov_b32_e32 v88, v95
	v_add_f32_e32 v95, v88, v94
	v_mov_b32_e32 v94, v104
	v_fmamk_f32 v86, v86, 0x3e38aa3b, v119
	v_exp_f32_e32 v89, v89
	v_fmamk_f32 v87, v87, 0x3e38aa3b, v119
	v_exp_f32_e32 v90, v90
	v_fmamk_f32 v80, v80, 0x3e38aa3b, v119
	v_exp_f32_e32 v91, v91
	v_fmamk_f32 v81, v81, 0x3e38aa3b, v119
	v_exp_f32_e32 v84, v84
	v_add_f32_e32 v95, v94, v95
	v_exp_f32_e32 v85, v85
	v_add_f32_e32 v95, v89, v95
	v_fmamk_f32 v82, v82, 0x3e38aa3b, v119
	v_exp_f32_e32 v104, v86
	v_mov_b32_e32 v86, v85
	v_mov_b32_e32 v85, v104
	v_add_f32_e32 v95, v90, v95
	v_exp_f32_e32 v87, v87
	v_add_f32_e32 v95, v91, v95
	v_add_f32_e32 v95, v84, v95
	v_exp_f32_e32 v104, v80
	v_mov_b32_e32 v80, v87
	v_mov_b32_e32 v87, v104
	v_add_f32_e32 v95, v86, v95
	v_exp_f32_e32 v81, v81
	v_add_f32_e32 v95, v85, v95
	v_exp_f32_e32 v82, v82
	v_add_f32_e32 v95, v80, v95
	v_add_f32_e32 v95, v87, v95
	v_fmamk_f32 v83, v83, 0x3e38aa3b, v119
	v_add_f32_e32 v95, v81, v95
	v_add_f32_e32 v103, v82, v95
	v_fmamk_f32 v76, v76, 0x3e38aa3b, v119
	v_exp_f32_e32 v83, v83
	v_fmamk_f32 v77, v77, 0x3e38aa3b, v119
	v_exp_f32_e32 v76, v76
	v_mov_b32_e32 v95, v83
	v_add_f32_e32 v83, v95, v103
	v_fmamk_f32 v78, v78, 0x3e38aa3b, v119
	v_exp_f32_e32 v77, v77
	v_fmamk_f32 v79, v79, 0x3e38aa3b, v119
	v_exp_f32_e32 v78, v78
	v_fmamk_f32 v72, v72, 0x3e38aa3b, v119
	v_exp_f32_e32 v79, v79
	v_add_f32_e32 v83, v76, v83
	v_exp_f32_e32 v72, v72
	v_add_f32_e32 v83, v77, v83
	v_add_f32_e32 v83, v78, v83
	v_add_f32_e32 v103, v79, v83
	v_fmamk_f32 v73, v73, 0x3e38aa3b, v119
	v_mov_b32_e32 v83, v72
	v_add_f32_e32 v72, v83, v103
	v_fmamk_f32 v104, v105, 0x3e38aa3b, v119
	v_exp_f32_e32 v73, v73
	v_fmamk_f32 v106, v106, 0x3e38aa3b, v119
	v_exp_f32_e32 v104, v104
	v_mov_b32_e32 v103, v73
	v_add_f32_e32 v72, v103, v72
	v_fmamk_f32 v73, v107, 0x3e38aa3b, v119
	v_add_f32_e32 v72, v104, v72
	v_fmamk_f32 v75, v75, 0x3e38aa3b, v119
	v_exp_f32_e32 v73, v73
	v_fmamk_f32 v74, v74, 0x3e38aa3b, v119
	v_exp_f32_e32 v106, v106
	v_mov_b32_e32 v105, v73
	v_add_f32_e32 v73, v105, v72
	v_mov_b32_e32 v72, v106
	v_add_f32_e32 v73, v72, v73
	v_exp_f32_e32 v75, v75
	v_fmamk_f32 v71, v71, 0x3e38aa3b, v119
	v_fmamk_f32 v70, v70, 0x3e38aa3b, v119
	v_exp_f32_e32 v107, v74
	v_mov_b32_e32 v74, v75
	v_add_f32_e32 v75, v74, v73
	v_mov_b32_e32 v73, v107
	v_fmamk_f32 v69, v69, 0x3e38aa3b, v119
	v_exp_f32_e32 v71, v71
	v_fmamk_f32 v68, v68, 0x3e38aa3b, v119
	v_fmamk_f32 v67, v67, 0x3e38aa3b, v119
	v_exp_f32_e32 v107, v70
	v_mov_b32_e32 v70, v71
	v_mov_b32_e32 v71, v107
	v_fmamk_f32 v66, v66, 0x3e38aa3b, v119
	v_exp_f32_e32 v69, v69
	v_fmamk_f32 v65, v65, 0x3e38aa3b, v119
	v_fmamk_f32 v64, v64, 0x3e38aa3b, v119
	v_exp_f32_e32 v107, v68
	v_mov_b32_e32 v68, v69
	v_mov_b32_e32 v69, v107
	v_fmamk_f32 v63, v63, 0x3e38aa3b, v119
	v_exp_f32_e32 v67, v67
	v_fmamk_f32 v62, v62, 0x3e38aa3b, v119
	v_exp_f32_e32 v66, v66
	v_fmamk_f32 v61, v61, 0x3e38aa3b, v119
	v_exp_f32_e32 v65, v65
	v_fmamk_f32 v60, v60, 0x3e38aa3b, v119
	v_fmamk_f32 v59, v59, 0x3e38aa3b, v119
	v_exp_f32_e32 v107, v64
	v_mov_b32_e32 v64, v65
	v_mov_b32_e32 v65, v107
	v_fmamk_f32 v58, v58, 0x3e38aa3b, v119
	v_exp_f32_e32 v63, v63
	v_fmamk_f32 v57, v57, 0x3e38aa3b, v119
	v_fmamk_f32 v56, v56, 0x3e38aa3b, v119
	v_exp_f32_e32 v107, v62
	v_mov_b32_e32 v62, v63
	v_mov_b32_e32 v63, v107
	v_fmamk_f32 v55, v55, 0x3e38aa3b, v119
	v_exp_f32_e32 v61, v61
	v_fmamk_f32 v54, v54, 0x3e38aa3b, v119
	v_fmamk_f32 v53, v53, 0x3e38aa3b, v119
	v_exp_f32_e32 v107, v60
	v_mov_b32_e32 v60, v61
	v_mov_b32_e32 v61, v107
	v_fmamk_f32 v52, v52, 0x3e38aa3b, v119
	v_exp_f32_e32 v59, v59
	v_fmamk_f32 v51, v51, 0x3e38aa3b, v119
	v_exp_f32_e32 v58, v58
	v_fmamk_f32 v50, v50, 0x3e38aa3b, v119
	v_exp_f32_e32 v57, v57
	v_fmamk_f32 v49, v49, 0x3e38aa3b, v119
	v_exp_f32_e32 v56, v56
	v_fmamk_f32 v48, v48, 0x3e38aa3b, v119
	v_exp_f32_e32 v55, v55
	v_fmamk_f32 v46, v46, 0x3e38aa3b, v119
	v_fmamk_f32 v45, v45, 0x3e38aa3b, v119
	v_exp_f32_e32 v107, v54
	v_mov_b32_e32 v54, v55
	v_mov_b32_e32 v55, v107
	v_fmamk_f32 v44, v44, 0x3e38aa3b, v119
; #define LAS __attribute__((address_space(3)))
; __device__ __forceinline__ unsigned cvt_pk_bf16_mfma(float lo, float hi) { const f32x2 v = {lo, hi}; return __builtin_bit_cast(unsigned, __builtin_convertvector(v, bf16v2_t)); }
; __device__ void attn_mfma(const Params& p, int l, const bf16_t* proj, bf16_t* y0, LAS unsigned char* lds) {
;     ...
;             float sum = 0.f; const float mxl = mx * 1.44269504f;
; #pragma unroll
;             for (int kt = 0; kt < 24; ++kt)
; #pragma unroll
;                 for (int r = 0; r < 4; ++r) { const float pr = exp2f(fmaf(sacc[kt][r], 1.44269504f, -mxl)); sacc[kt][r] = pr; sum += pr; }
;             sum += __shfl_xor(sum, 16); sum += __shfl_xor(sum, 32);
;             const float inv = 1.0f / (sum + __expf(sink - mx));
;             f32x4 oacc[4];
; #pragma unroll
;             for (int dt = 0; dt < 4; ++dt) oacc[dt] = (f32x4){0.f, 0.f, 0.f, 0.f};
; #pragma unroll
;             for (int i = 0; i < 12; ++i) {
;                 u32x4 pw; pw.x = cvt_pk_bf16_mfma(sacc[2 * i][0], sacc[2 * i][1]); pw.y = cvt_pk_bf16_mfma(sacc[2 * i][2], sacc[2 * i][3]); pw.z = cvt_pk_bf16_mfma(sacc[2 * i + 1][0], sacc[2 * i + 1][1]); pw.w = cvt_pk_bf16_mfma(sacc[2 * i + 1][2], sacc[2 * i + 1][3]);
;                 const bf16x8 pf = __builtin_bit_cast(bf16x8, pw);
; #pragma unroll
;                 for (int dt = 0; dt < 4; ++dt) { const LAS bf16_t* vp = Vt + (dt * 16 + fr) * VP + 32 * i + 4 * g;
;                     const u32x2 lo = *(const LAS u32x2*)vp, hi = *(const LAS u32x2*)(vp + 16);
;                     u32x4 vw; vw.x = lo.x; vw.y = lo.y; vw.z = hi.x; vw.w = hi.y;
;                     oacc[dt] = __builtin_amdgcn_mfma_f32_16x16x32_bf16(__builtin_bit_cast(bf16x8, vw), pf, oacc[dt], 0, 0, 0); }
;                 if (i & 1) __builtin_amdgcn_sched_barrier(0); }
	v_exp_f32_e32 v53, v53
	v_fmamk_f32 v41, v41, 0x3e38aa3b, v119
	v_fmamk_f32 v40, v40, 0x3e38aa3b, v119
	v_exp_f32_e32 v107, v52
	v_mov_b32_e32 v52, v53
	v_mov_b32_e32 v53, v107
	v_fmamk_f32 v36, v36, 0x3e38aa3b, v119
	v_exp_f32_e32 v51, v51
	v_fmamk_f32 v37, v37, 0x3e38aa3b, v119
	v_exp_f32_e32 v50, v50
	v_fmamk_f32 v38, v38, 0x3e38aa3b, v119
	v_exp_f32_e32 v49, v49
	v_fmamk_f32 v39, v39, 0x3e38aa3b, v119
	v_fmamk_f32 v32, v32, 0x3e38aa3b, v119
	v_exp_f32_e32 v107, v48
	v_mov_b32_e32 v48, v49
	v_mov_b32_e32 v49, v107
	v_fmamk_f32 v33, v33, 0x3e38aa3b, v119
	v_exp_f32_e32 v46, v46
	v_fmamk_f32 v34, v34, 0x3e38aa3b, v119
	v_fmamk_f32 v35, v35, 0x3e38aa3b, v119
	v_exp_f32_e32 v107, v45
	v_mov_b32_e32 v45, v46
	v_mov_b32_e32 v46, v107
	v_fmamk_f32 v28, v28, 0x3e38aa3b, v119
	v_exp_f32_e32 v44, v44
	v_fmamk_f32 v29, v29, 0x3e38aa3b, v119
	v_fmamk_f32 v30, v30, 0x3e38aa3b, v119
	v_exp_f32_e32 v107, v41
	v_mov_b32_e32 v41, v44
	v_mov_b32_e32 v44, v107
	v_add_f32_e32 v75, v73, v75
	v_exp_f32_e32 v40, v40
	v_add_f32_e32 v75, v70, v75
	v_exp_f32_e32 v36, v36
	v_add_f32_e32 v75, v71, v75
	v_exp_f32_e32 v37, v37
	v_add_f32_e32 v75, v68, v75
	v_add_f32_e32 v75, v69, v75
	v_exp_f32_e32 v107, v38
	v_mov_b32_e32 v38, v37
	v_mov_b32_e32 v37, v107
	v_fmamk_f32 v31, v31, 0x3e38aa3b, v119
	v_exp_f32_e32 v39, v39
	v_add_f32_e32 v75, v67, v75
	v_add_f32_e32 v75, v66, v75
	v_exp_f32_e32 v107, v32
	v_mov_b32_e32 v32, v39
	v_mov_b32_e32 v39, v107
	v_add_f32_e32 v75, v64, v75
	v_exp_f32_e32 v33, v33
	v_fmamk_f32 v24, v24, 0x3e38aa3b, v119
	v_exp_f32_e32 v34, v34
	v_add_f32_e32 v75, v65, v75
	v_exp_f32_e32 v35, v35
	v_add_f32_e32 v75, v62, v75
	v_exp_f32_e32 v28, v28
	v_add_f32_e32 v75, v63, v75
	v_exp_f32_e32 v29, v29
	v_add_f32_e32 v75, v60, v75
	v_exp_f32_e32 v30, v30
	v_fmamk_f32 v25, v25, 0x3e38aa3b, v119
	v_exp_f32_e32 v31, v31
	v_add_f32_e32 v75, v61, v75
	v_add_f32_e32 v75, v59, v75
	v_exp_f32_e32 v107, v24
	v_mov_b32_e32 v24, v31
	v_fmamk_f32 v26, v26, 0x3e38aa3b, v119
	v_add_f32_e32 v75, v58, v75
	v_add_f32_e32 v75, v57, v75
	v_mov_b32_e32 v31, v107
	v_add_f32_e32 v75, v56, v75
	v_exp_f32_e32 v25, v25
	v_add_f32_e32 v75, v54, v75
	v_exp_f32_e32 v26, v26
	v_add_f32_e32 v75, v55, v75
	v_add_f32_e32 v75, v52, v75
	v_fmamk_f32 v27, v27, 0x3e38aa3b, v119
	v_add_f32_e32 v75, v53, v75
	v_add_f32_e32 v75, v51, v75
	v_fmamk_f32 v20, v20, 0x3e38aa3b, v119
	v_add_f32_e32 v75, v50, v75
	v_add_f32_e32 v75, v48, v75
	v_add_f32_e32 v75, v49, v75
	v_exp_f32_e32 v27, v27
	v_add_f32_e32 v75, v45, v75
	v_exp_f32_e32 v20, v20
	v_add_f32_e32 v75, v46, v75
	v_add_f32_e32 v75, v41, v75
	v_fmamk_f32 v21, v21, 0x3e38aa3b, v119
	v_add_f32_e32 v75, v44, v75
	v_add_f32_e32 v75, v40, v75
	v_add_f32_e32 v75, v36, v75
	v_add_f32_e32 v75, v38, v75
	v_exp_f32_e32 v21, v21
	v_fmamk_f32 v22, v22, 0x3e38aa3b, v119
	v_add_f32_e32 v75, v37, v75
	v_add_f32_e32 v75, v32, v75
	v_add_f32_e32 v75, v39, v75
	v_fmamk_f32 v23, v23, 0x3e38aa3b, v119
	v_add_f32_e32 v75, v33, v75
	v_exp_f32_e32 v107, v22
	v_mov_b32_e32 v22, v21
	v_add_f32_e32 v75, v34, v75
	v_add_f32_e32 v75, v35, v75
	v_fmamk_f32 v16, v16, 0x3e38aa3b, v119
	v_add_f32_e32 v75, v28, v75
	v_exp_f32_e32 v23, v23
	v_add_f32_e32 v75, v29, v75
	v_mov_b32_e32 v21, v107
	v_add_f32_e32 v75, v30, v75
	v_add_f32_e32 v75, v24, v75
	v_exp_f32_e32 v107, v16
	v_fmamk_f32 v17, v17, 0x3e38aa3b, v119
	v_add_f32_e32 v75, v31, v75
	v_mov_b32_e32 v16, v23
	v_add_f32_e32 v75, v25, v75
	v_fmamk_f32 v18, v18, 0x3e38aa3b, v119
	v_add_f32_e32 v75, v26, v75
	v_add_f32_e32 v75, v27, v75
	v_mov_b32_e32 v23, v107
	v_add_f32_e32 v75, v20, v75
	v_exp_f32_e32 v17, v17
	v_add_f32_e32 v75, v22, v75
	v_exp_f32_e32 v18, v18
	v_add_f32_e32 v75, v21, v75
	v_add_f32_e32 v75, v16, v75
	v_add_f32_e32 v75, v23, v75
	v_fmamk_f32 v19, v19, 0x3e38aa3b, v119
	v_add_f32_e32 v75, v17, v75
	v_add_f32_e32 v106, v18, v75
	v_fmamk_f32 v12, v12, 0x3e38aa3b, v119
	v_exp_f32_e32 v19, v19
	v_fmamk_f32 v13, v13, 0x3e38aa3b, v119
	v_exp_f32_e32 v12, v12
	v_mov_b32_e32 v75, v19
	v_add_f32_e32 v19, v75, v106
	v_fmamk_f32 v14, v14, 0x3e38aa3b, v119
	v_exp_f32_e32 v13, v13
	v_fmamk_f32 v15, v15, 0x3e38aa3b, v119
	v_exp_f32_e32 v14, v14
	v_fmamk_f32 v42, v42, 0x3e38aa3b, v119
	v_exp_f32_e32 v15, v15
	v_add_f32_e32 v19, v12, v19
	v_exp_f32_e32 v42, v42
	v_add_f32_e32 v19, v13, v19
	v_add_f32_e32 v19, v14, v19
	v_add_f32_e32 v106, v15, v19
	v_fmamk_f32 v43, v43, 0x3e38aa3b, v119
	v_mov_b32_e32 v19, v42
	v_add_f32_e32 v42, v19, v106
	v_fmamk_f32 v10, v10, 0x3e38aa3b, v119
	v_exp_f32_e32 v43, v43
	v_fmac_f32_e32 v119, 0x3e38aa3b, v47
	v_add_u32_e32 v47, 0xd800, v142
	v_exp_f32_e32 v107, v10
	v_mov_b32_e32 v10, v43
	v_add_f32_e32 v106, v10, v42
	v_mov_b32_e32 v42, v107
	v_cvt_pk_bf16_f32 v154, v9, v100
	v_add_u32_e32 v9, 0xd800, v143
	v_cvt_pk_bf16_f32 v156, v96, v97
	v_add_u32_e32 v43, 0xd800, v144
	v_add_u32_e32 v96, 0xd800, v145
	ds_read_b64 v[150:151], v47
	ds_read_b64 v[152:153], v47 offset:32
	v_cvt_pk_bf16_f32 v155, v101, v102
	ds_read_b64 v[158:159], v9
	ds_read_b64 v[160:161], v9 offset:32
	v_cvt_pk_bf16_f32 v157, v98, v99
	ds_read_b64 v[98:99], v43
	ds_read_b64 v[100:101], v43 offset:32
	ds_read_b64 v[162:163], v96
	ds_read_b64 v[164:165], v96 offset:32
	ds_read_b64 v[166:167], v47 offset:64
	ds_read_b64 v[168:169], v47 offset:96
	s_waitcnt lgkmcnt(8)
	v_mfma_f32_16x16x32_bf16 v[150:153], v[150:153], v[154:157], 0
	v_exp_f32_e32 v97, v119
	v_add_f32_e32 v102, v42, v106
	s_waitcnt lgkmcnt(6)
	v_mfma_f32_16x16x32_bf16 v[158:161], v[158:161], v[154:157], 0
	v_cvt_pk_bf16_f32 v170, v11, v92
	v_cvt_pk_bf16_f32 v171, v93, v88
	s_waitcnt lgkmcnt(4)
; #define LAS __attribute__((address_space(3)))
; __device__ __forceinline__ unsigned cvt_pk_bf16_mfma(float lo, float hi) { const f32x2 v = {lo, hi}; return __builtin_bit_cast(unsigned, __builtin_convertvector(v, bf16v2_t)); }
; __device__ void attn_mfma(const Params& p, int l, const bf16_t* proj, bf16_t* y0, LAS unsigned char* lds) {
;     ...
;             sum += __shfl_xor(sum, 16); sum += __shfl_xor(sum, 32);
;             const float inv = 1.0f / (sum + __expf(sink - mx));
;             f32x4 oacc[4];
; #pragma unroll
;             for (int dt = 0; dt < 4; ++dt) oacc[dt] = (f32x4){0.f, 0.f, 0.f, 0.f};
; #pragma unroll
;             for (int i = 0; i < 12; ++i) {
;                 u32x4 pw; pw.x = cvt_pk_bf16_mfma(sacc[2 * i][0], sacc[2 * i][1]); pw.y = cvt_pk_bf16_mfma(sacc[2 * i][2], sacc[2 * i][3]); pw.z = cvt_pk_bf16_mfma(sacc[2 * i + 1][0], sacc[2 * i + 1][1]); pw.w = cvt_pk_bf16_mfma(sacc[2 * i + 1][2], sacc[2 * i + 1][3]);
;                 const bf16x8 pf = __builtin_bit_cast(bf16x8, pw);
; #pragma unroll
;                 for (int dt = 0; dt < 4; ++dt) { const LAS bf16_t* vp = Vt + (dt * 16 + fr) * VP + 32 * i + 4 * g;
;                     const u32x2 lo = *(const LAS u32x2*)vp, hi = *(const LAS u32x2*)(vp + 16);
;                     u32x4 vw; vw.x = lo.x; vw.y = lo.y; vw.z = hi.x; vw.w = hi.y;
;                     oacc[dt] = __builtin_amdgcn_mfma_f32_16x16x32_bf16(__builtin_bit_cast(bf16x8, vw), pf, oacc[dt], 0, 0, 0); }
;                 if (i & 1) __builtin_amdgcn_sched_barrier(0); }
	v_mfma_f32_16x16x32_bf16 v[98:101], v[98:101], v[154:157], 0
	v_cvt_pk_bf16_f32 v172, v94, v89
	v_cvt_pk_bf16_f32 v173, v90, v91
	v_add_f32_e32 v102, v97, v102
	s_waitcnt lgkmcnt(2)
	v_mfma_f32_16x16x32_bf16 v[154:157], v[162:165], v[154:157], 0
	ds_read_b64 v[162:163], v9 offset:64
	ds_read_b64 v[164:165], v9 offset:96
	ds_bpermute_b32 v106, v121, v102
	v_fmamk_f32 v8, v8, 0xbe000000, v146
	s_waitcnt lgkmcnt(3)
	v_mfma_f32_16x16x32_bf16 v[88:91], v[166:169], v[170:173], v[150:153]
	v_mul_f32_e32 v8, 0x3fb8aa3b, v8
	v_exp_f32_e32 v8, v8
	s_waitcnt lgkmcnt(0)
	v_add_f32_e32 v11, v102, v106
	ds_read_b64 v[150:151], v43 offset:64
	ds_read_b64 v[152:153], v43 offset:96
	v_mfma_f32_16x16x32_bf16 v[158:161], v[162:165], v[170:173], v[158:161]
	ds_read_b64 v[162:163], v96 offset:64
	ds_read_b64 v[164:165], v96 offset:96
	v_mov_b32_e32 v92, v11
	s_waitcnt lgkmcnt(0)
	s_nop 1
	v_permlane32_swap_b32_e32 v92, v11
	v_add_f32_e32 v11, v11, v92
	v_mfma_f32_16x16x32_bf16 v[98:101], v[150:153], v[170:173], v[98:101]
	v_add_f32_e32 v106, v8, v11
	v_mfma_f32_16x16x32_bf16 v[150:153], v[162:165], v[170:173], v[154:157]
	v_cvt_pk_bf16_f32 v84, v84, v86
	v_cvt_pk_bf16_f32 v86, v87, v81
	v_cvt_pk_bf16_f32 v87, v82, v95
	ds_read_b64 v[92:93], v43 offset:128
	ds_read_b64 v[94:95], v43 offset:160
	ds_read_b64 v[154:155], v47 offset:128
	ds_read_b64 v[156:157], v47 offset:160
	v_cvt_pk_bf16_f32 v85, v85, v80
	ds_read_b64 v[162:163], v9 offset:128
	ds_read_b64 v[164:165], v9 offset:160
	v_cvt_pk_bf16_f32 v76, v76, v77
	v_cvt_pk_bf16_f32 v77, v78, v79
	s_waitcnt lgkmcnt(4)
	v_mfma_f32_16x16x32_bf16 v[92:95], v[92:95], v[84:87], v[98:101]
	s_nop 2
	ds_read_b64 v[98:99], v47 offset:192
	ds_read_b64 v[100:101], v47 offset:224
	v_cvt_pk_bf16_f32 v78, v83, v103
	v_cvt_pk_bf16_f32 v79, v104, v105
	s_waitcnt lgkmcnt(4)
	v_mfma_f32_16x16x32_bf16 v[88:91], v[154:157], v[84:87], v[88:91]
	s_waitcnt lgkmcnt(0)
	v_mfma_f32_16x16x32_bf16 v[80:83], v[98:101], v[76:79], v[88:91]
	ds_read_b64 v[98:99], v43 offset:192
	ds_read_b64 v[100:101], v43 offset:224
	s_nop 4
	ds_read_b64 v[88:89], v9 offset:192
	ds_read_b64 v[90:91], v9 offset:224
	v_mfma_f32_16x16x32_bf16 v[154:157], v[162:165], v[84:87], v[158:161]
	s_nop 2
	ds_read_b64 v[158:159], v96 offset:128
	ds_read_b64 v[160:161], v96 offset:160
	s_waitcnt lgkmcnt(4)
	v_mfma_f32_16x16x32_bf16 v[92:95], v[98:101], v[76:79], v[92:95]
	ds_read_b64 v[98:99], v96 offset:192
	ds_read_b64 v[100:101], v96 offset:224
	s_waitcnt lgkmcnt(2)
	v_mfma_f32_16x16x32_bf16 v[84:87], v[158:161], v[84:87], v[150:153]
	v_mfma_f32_16x16x32_bf16 v[88:91], v[88:91], v[76:79], v[154:157]
	s_waitcnt lgkmcnt(0)
	v_mfma_f32_16x16x32_bf16 v[76:79], v[98:101], v[76:79], v[84:87]
	s_nop 4
	ds_read_b64 v[84:85], v47 offset:256
	ds_read_b64 v[86:87], v47 offset:288
	v_cvt_pk_bf16_f32 v98, v72, v74
	v_cvt_pk_bf16_f32 v99, v73, v70
	v_cvt_pk_bf16_f32 v100, v71, v68
	v_cvt_pk_bf16_f32 v101, v69, v67
	ds_read_b64 v[102:103], v9 offset:256
	ds_read_b64 v[104:105], v9 offset:288
	v_cvt_pk_bf16_f32 v64, v66, v64
	v_cvt_pk_bf16_f32 v65, v65, v62
	v_cvt_pk_bf16_f32 v66, v63, v60
	s_waitcnt lgkmcnt(2)
	v_mfma_f32_16x16x32_bf16 v[68:71], v[84:87], v[98:101], v[80:83]
	v_cvt_pk_bf16_f32 v67, v61, v59
	s_nop 1
	ds_read_b64 v[80:81], v43 offset:256
	ds_read_b64 v[82:83], v43 offset:288
	s_waitcnt lgkmcnt(2)
	v_mfma_f32_16x16x32_bf16 v[84:87], v[102:105], v[98:101], v[88:91]
	s_waitcnt lgkmcnt(0)
	v_mfma_f32_16x16x32_bf16 v[80:83], v[80:83], v[98:101], v[92:95]
	s_nop 2
	ds_read_b64 v[92:93], v47 offset:320
	ds_read_b64 v[94:95], v47 offset:352
	ds_read_b64 v[88:89], v96 offset:256
	ds_read_b64 v[90:91], v96 offset:288
	s_waitcnt lgkmcnt(0)
	v_mfma_f32_16x16x32_bf16 v[76:79], v[88:91], v[98:101], v[76:79]
	v_mfma_f32_16x16x32_bf16 v[60:63], v[92:95], v[64:67], v[68:71]
	s_nop 2
	ds_read_b64 v[68:69], v9 offset:320
	ds_read_b64 v[70:71], v9 offset:352
	s_waitcnt lgkmcnt(0)
	v_mfma_f32_16x16x32_bf16 v[68:71], v[68:71], v[64:67], v[84:87]
	s_nop 2
	ds_read_b64 v[84:85], v43 offset:320
	ds_read_b64 v[86:87], v43 offset:352
	s_waitcnt lgkmcnt(0)
	v_mfma_f32_16x16x32_bf16 v[80:83], v[84:87], v[64:67], v[80:83]
	ds_read_b64 v[84:85], v96 offset:320
	ds_read_b64 v[86:87], v96 offset:352
	s_waitcnt lgkmcnt(0)
	v_mfma_f32_16x16x32_bf16 v[64:67], v[84:87], v[64:67], v[76:79]
	s_nop 2
	ds_read_b64 v[76:77], v47 offset:384
	ds_read_b64 v[78:79], v47 offset:416
	ds_read_b64 v[88:89], v9 offset:384
	ds_read_b64 v[90:91], v9 offset:416
	v_cvt_pk_bf16_f32 v84, v58, v57
	v_cvt_pk_bf16_f32 v85, v56, v54
	v_cvt_pk_bf16_f32 v86, v55, v52
	v_cvt_pk_bf16_f32 v87, v53, v51
	ds_read_b64 v[56:57], v43 offset:384
	ds_read_b64 v[58:59], v43 offset:416
	v_cvt_pk_bf16_f32 v48, v50, v48
	v_cvt_pk_bf16_f32 v49, v49, v45
	s_waitcnt lgkmcnt(4)
	v_mfma_f32_16x16x32_bf16 v[52:55], v[76:79], v[84:87], v[60:63]
	v_cvt_pk_bf16_f32 v50, v46, v41
	v_cvt_pk_bf16_f32 v51, v44, v40
	ds_read_b64 v[76:77], v47 offset:448
	ds_read_b64 v[78:79], v47 offset:480
	s_waitcnt lgkmcnt(4)
	v_mfma_f32_16x16x32_bf16 v[60:63], v[88:91], v[84:87], v[68:71]
	s_nop 2
	ds_read_b64 v[68:69], v96 offset:384
	ds_read_b64 v[70:71], v96 offset:416
	s_waitcnt lgkmcnt(0)
	v_mfma_f32_16x16x32_bf16 v[64:67], v[68:71], v[84:87], v[64:67]
	ds_read_b64 v[68:69], v9 offset:448
	ds_read_b64 v[70:71], v9 offset:480
	s_waitcnt lgkmcnt(0)
; #define LAS __attribute__((address_space(3)))
; __device__ __forceinline__ unsigned cvt_pk_bf16(float lo, float hi) { unsigned r; asm("v_cvt_pk_bf16_f32 %0, %1, %2" : "=v"(r) : "v"(lo), "v"(hi)); return r; }
; __device__ __forceinline__ unsigned cvt_pk_bf16_mfma(float lo, float hi) { const f32x2 v = {lo, hi}; return __builtin_bit_cast(unsigned, __builtin_convertvector(v, bf16v2_t)); }
; __device__ void attn_mfma(const Params& p, int l, const bf16_t* proj, bf16_t* y0, LAS unsigned char* lds) {
;     ...
;             const float inv = 1.0f / (sum + __expf(sink - mx));
;             f32x4 oacc[4];
; #pragma unroll
;             for (int dt = 0; dt < 4; ++dt) oacc[dt] = (f32x4){0.f, 0.f, 0.f, 0.f};
; #pragma unroll
;             for (int i = 0; i < 12; ++i) {
;                 u32x4 pw; pw.x = cvt_pk_bf16_mfma(sacc[2 * i][0], sacc[2 * i][1]); pw.y = cvt_pk_bf16_mfma(sacc[2 * i][2], sacc[2 * i][3]); pw.z = cvt_pk_bf16_mfma(sacc[2 * i + 1][0], sacc[2 * i + 1][1]); pw.w = cvt_pk_bf16_mfma(sacc[2 * i + 1][2], sacc[2 * i + 1][3]);
;                 const bf16x8 pf = __builtin_bit_cast(bf16x8, pw);
; #pragma unroll
;                 for (int dt = 0; dt < 4; ++dt) { const LAS bf16_t* vp = Vt + (dt * 16 + fr) * VP + 32 * i + 4 * g;
;                     const u32x2 lo = *(const LAS u32x2*)vp, hi = *(const LAS u32x2*)(vp + 16);
;                     u32x4 vw; vw.x = lo.x; vw.y = lo.y; vw.z = hi.x; vw.w = hi.y;
;                     oacc[dt] = __builtin_amdgcn_mfma_f32_16x16x32_bf16(__builtin_bit_cast(bf16x8, vw), pf, oacc[dt], 0, 0, 0); }
;                 if (i & 1) __builtin_amdgcn_sched_barrier(0); }
; #pragma unroll
;             for (int dt = 0; dt < 4; ++dt) { u32x2 w; w.x = cvt_pk_bf16(oacc[dt][0] * inv, oacc[dt][1] * inv); w.y = cvt_pk_bf16(oacc[dt][2] * inv, oacc[dt][3] * inv);
;                 *(u32x2*)(y0 + (size_t)t * 512 + hq * 64 + dt * 16 + 4 * g) = w; }
	v_mfma_f32_16x16x32_bf16 v[60:63], v[68:71], v[48:51], v[60:63]
	ds_read_b64 v[68:69], v43 offset:448
	ds_read_b64 v[70:71], v43 offset:480
	v_mfma_f32_16x16x32_bf16 v[56:59], v[56:59], v[84:87], v[80:83]
	s_waitcnt lgkmcnt(0)
	v_mfma_f32_16x16x32_bf16 v[56:59], v[68:71], v[48:51], v[56:59]
	ds_read_b64 v[68:69], v96 offset:448
	ds_read_b64 v[70:71], v96 offset:480
	v_mfma_f32_16x16x32_bf16 v[52:55], v[76:79], v[48:51], v[52:55]
	s_waitcnt lgkmcnt(0)
	v_mfma_f32_16x16x32_bf16 v[48:51], v[68:71], v[48:51], v[64:67]
	s_nop 2
	ds_read_b64 v[64:65], v47 offset:512
	ds_read_b64 v[66:67], v47 offset:544
	v_cvt_pk_bf16_f32 v36, v36, v38
	v_cvt_pk_bf16_f32 v37, v37, v32
	v_cvt_pk_bf16_f32 v38, v39, v33
	v_cvt_pk_bf16_f32 v39, v34, v35
	ds_read_b64 v[68:69], v9 offset:512
	ds_read_b64 v[70:71], v9 offset:544
	v_cvt_pk_bf16_f32 v28, v28, v29
	v_cvt_pk_bf16_f32 v29, v30, v24
	v_cvt_pk_bf16_f32 v30, v31, v25
	s_waitcnt lgkmcnt(2)
	v_mfma_f32_16x16x32_bf16 v[32:35], v[64:67], v[36:39], v[52:55]
	ds_read_b64 v[64:65], v96 offset:512
	ds_read_b64 v[66:67], v96 offset:544
	v_cvt_pk_bf16_f32 v31, v26, v27
	s_nop 0
	ds_read_b64 v[52:53], v43 offset:512
	ds_read_b64 v[54:55], v43 offset:544
	s_waitcnt lgkmcnt(4)
	v_mfma_f32_16x16x32_bf16 v[60:63], v[68:71], v[36:39], v[60:63]
	s_waitcnt lgkmcnt(0)
	v_mfma_f32_16x16x32_bf16 v[52:55], v[52:55], v[36:39], v[56:59]
	s_nop 2
	ds_read_b64 v[56:57], v47 offset:576
	ds_read_b64 v[58:59], v47 offset:608
	v_mfma_f32_16x16x32_bf16 v[36:39], v[64:67], v[36:39], v[48:51]
	s_nop 2
	ds_read_b64 v[48:49], v43 offset:576
	ds_read_b64 v[50:51], v43 offset:608
	s_waitcnt lgkmcnt(2)
	v_mfma_f32_16x16x32_bf16 v[24:27], v[56:59], v[28:31], v[32:35]
	s_nop 2
	ds_read_b64 v[32:33], v9 offset:576
	ds_read_b64 v[34:35], v9 offset:608
	s_waitcnt lgkmcnt(2)
	v_mfma_f32_16x16x32_bf16 v[48:51], v[48:51], v[28:31], v[52:55]
	s_nop 2
	ds_read_b64 v[52:53], v96 offset:576
	ds_read_b64 v[54:55], v96 offset:608
	s_waitcnt lgkmcnt(2)
	v_mfma_f32_16x16x32_bf16 v[32:35], v[32:35], v[28:31], v[60:63]
	s_waitcnt lgkmcnt(0)
	v_mfma_f32_16x16x32_bf16 v[28:31], v[52:55], v[28:31], v[36:39]
	s_nop 2
	ds_read_b64 v[36:37], v47 offset:640
	ds_read_b64 v[38:39], v47 offset:672
	ds_read_b64 v[52:53], v9 offset:640
	ds_read_b64 v[54:55], v9 offset:672
	v_cvt_pk_bf16_f32 v20, v20, v22
	v_cvt_pk_bf16_f32 v21, v21, v16
	v_cvt_pk_bf16_f32 v22, v23, v17
	v_cvt_pk_bf16_f32 v23, v18, v75
	ds_read_b64 v[44:45], v47 offset:704
	ds_read_b64 v[46:47], v47 offset:736
	v_cvt_pk_bf16_f32 v12, v12, v13
	v_cvt_pk_bf16_f32 v13, v14, v15
	s_waitcnt lgkmcnt(4)
	v_mfma_f32_16x16x32_bf16 v[24:27], v[36:39], v[20:23], v[24:27]
	ds_read_b64 v[36:37], v43 offset:640
	ds_read_b64 v[38:39], v43 offset:672
	v_cvt_pk_bf16_f32 v14, v19, v10
	ds_read_b64 v[10:11], v9 offset:736
	ds_read_b64 v[8:9], v9 offset:704
	s_waitcnt lgkmcnt(6)
	v_mfma_f32_16x16x32_bf16 v[32:35], v[52:55], v[20:23], v[32:35]
	ds_read_b64 v[52:53], v96 offset:640
	ds_read_b64 v[54:55], v96 offset:672
	v_cvt_pk_bf16_f32 v15, v42, v97
	s_waitcnt lgkmcnt(4)
	v_mfma_f32_16x16x32_bf16 v[36:39], v[36:39], v[20:23], v[48:51]
	s_waitcnt lgkmcnt(0)
	v_mfma_f32_16x16x32_bf16 v[20:23], v[52:55], v[20:23], v[28:31]
	v_mfma_f32_16x16x32_bf16 v[16:19], v[44:47], v[12:15], v[24:27]
	s_nop 1
	ds_read_b64 v[28:29], v96 offset:704
	ds_read_b64 v[30:31], v96 offset:736
	ds_read_b64 v[24:25], v43 offset:704
	ds_read_b64 v[26:27], v43 offset:736
	v_mfma_f32_16x16x32_bf16 v[8:11], v[8:11], v[12:15], v[32:35]
	s_waitcnt lgkmcnt(0)
	v_mfma_f32_16x16x32_bf16 v[24:27], v[24:27], v[12:15], v[36:39]
	v_mfma_f32_16x16x32_bf16 v[12:15], v[28:31], v[12:15], v[20:23]
	s_nop 2
	v_div_scale_f32 v20, s[14:15], v106, v106, 1.0
	v_rcp_f32_e32 v21, v20
	v_div_scale_f32 v22, vcc, 1.0, v106, 1.0
	v_ashrrev_i32_e32 v119, 31, v118
	v_fma_f32 v23, -v20, v21, 1.0
	v_fmac_f32_e32 v21, v23, v21
	v_mul_f32_e32 v23, v22, v21
	v_fma_f32 v28, -v20, v23, v22
	v_fmac_f32_e32 v23, v28, v21
	v_fma_f32 v20, -v20, v23, v22
	v_div_fmas_f32 v20, v20, v21, v23
	v_div_fixup_f32 v22, v20, v106, 1.0
	v_mul_f32_e32 v8, v22, v8
	v_mul_f32_e32 v9, v22, v9
	v_lshlrev_b64 v[20:21], 10, v[118:119]
	v_cvt_pk_bf16_f32 v8, v8, v9
	v_mul_f32_e32 v9, v22, v10
	v_lshl_add_u64 v[20:21], v[116:117], 0, v[20:21]
	v_mul_f32_e32 v10, v22, v11
	v_cvt_pk_bf16_f32 v9, v9, v10
	global_store_dwordx2 v[20:21], v[8:9], off offset:32
	v_mul_f32_e32 v8, v22, v24
	v_mul_f32_e32 v9, v22, v25
	v_cvt_pk_bf16_f32 v8, v8, v9
	v_mul_f32_e32 v9, v22, v26
	v_mul_f32_e32 v10, v22, v27
	v_cvt_pk_bf16_f32 v9, v9, v10
	global_store_dwordx2 v[20:21], v[8:9], off offset:64
	v_mul_f32_e32 v8, v22, v12
	v_mul_f32_e32 v9, v22, v13
	v_cvt_pk_bf16_f32 v8, v8, v9
	v_mul_f32_e32 v9, v22, v14
	v_mul_f32_e32 v10, v22, v15
	v_cvt_pk_bf16_f32 v9, v9, v10
	v_mul_f32_e32 v16, v22, v16
	v_mul_f32_e32 v17, v22, v17
	global_store_dwordx2 v[20:21], v[8:9], off offset:96
	s_add_i32 s12, s12, 16
	s_waitcnt vmcnt(3)
	v_mov_b64_e32 v[10:11], v[6:7]
	v_mov_b64_e32 v[102:103], v[2:3]
	v_cvt_pk_bf16_f32 v16, v16, v17
	v_mul_f32_e32 v17, v22, v18
	s_cmp_eq_u32 s12, 64
	v_mov_b64_e32 v[8:9], v[4:5]
	v_mov_b64_e32 v[100:101], v[0:1]
	v_mul_f32_e32 v18, v22, v19
	v_cvt_pk_bf16_f32 v17, v17, v18
	global_store_dwordx2 v[20:21], v[16:17], off
	s_cbranch_scc0 .LBB0_478
	s_add_i32 s11, s11, s59
	s_cmpk_gt_i32 s11, 0xff
	s_cbranch_scc0 .LBB0_459
